# SWIGLU GEMM epilogue rewritten by hand: batched rstd shuffles, packed f32 ops, software-pipelined so exp/rcp overlap the packed VALU work (same arithmetic)
# speedup vs baseline: 1.0136x; 1.0136x over previous
.LBB0_824:
	s_add_i32 s7, 0, 0x10000
	v_add_u32_e32 v145, s7, v153
	ds_read_b128 v[162:165], v145
	ds_read_b128 v[166:169], v145 offset:1024
	ds_read_b128 v[170:173], v145 offset:2048
	ds_read_b128 v[174:177], v145 offset:3072
	s_add_i32 s6, s0, 2
	s_cmp_eq_u32 s44, s0
	v_lshl_add_u64 v[150:151], v[148:149], 0, s[84:85]
	s_cselect_b64 vcc, -1, 0
	s_cselect_b32 s0, s22, s4
	v_cndmask_b32_e32 v151, v151, v147, vcc
	v_cndmask_b32_e32 v150, v150, v146, vcc
	s_cselect_b32 s1, s23, s5
	v_lshl_add_u64 v[210:211], v[148:149], 0, v[140:141]
	s_add_i32 m0, s28, 0xc000
	ds_read_b128 v[178:181], v157
	ds_read_b128 v[182:185], v157 offset:1024
	ds_read_b128 v[186:189], v157 offset:2048
	ds_read_b128 v[190:193], v157 offset:3072
	ds_read_b128 v[194:197], v157 offset:4096
	ds_read_b128 v[198:201], v157 offset:5120
	ds_read_b128 v[202:205], v157 offset:6144
	ds_read_b128 v[206:209], v157 offset:7168
	global_load_lds_dwordx4 v[210:211], off
	v_lshl_add_u64 v[210:211], v[148:149], 0, v[142:143]
	s_add_i32 m0, s28, 0xe000
	s_nop 0
	global_load_lds_dwordx4 v[210:211], off
	s_waitcnt lgkmcnt(8)
	s_barrier
	s_waitcnt lgkmcnt(0)
	s_waitcnt lgkmcnt(0)
	v_mfma_f32_16x16x32_bf16 v[126:129], v[162:165], v[178:181], v[126:129]
	v_mfma_f32_16x16x32_bf16 v[118:121], v[170:173], v[178:181], v[118:121]
	v_mfma_f32_16x16x32_bf16 v[110:113], v[162:165], v[186:189], v[110:113]
	v_mfma_f32_16x16x32_bf16 v[102:105], v[170:173], v[186:189], v[102:105]
	v_mfma_f32_16x16x32_bf16 v[94:97], v[162:165], v[194:197], v[94:97]
	v_mfma_f32_16x16x32_bf16 v[86:89], v[170:173], v[194:197], v[86:89]
	v_mfma_f32_16x16x32_bf16 v[78:81], v[162:165], v[202:205], v[78:81]
	v_mfma_f32_16x16x32_bf16 v[70:73], v[170:173], v[202:205], v[70:73]
	v_mfma_f32_16x16x32_bf16 v[126:129], v[166:169], v[182:185], v[126:129]
	v_mfma_f32_16x16x32_bf16 v[118:121], v[174:177], v[182:185], v[118:121]
	v_mfma_f32_16x16x32_bf16 v[110:113], v[166:169], v[190:193], v[110:113]
	v_mfma_f32_16x16x32_bf16 v[102:105], v[174:177], v[190:193], v[102:105]
	v_mfma_f32_16x16x32_bf16 v[94:97], v[166:169], v[198:201], v[94:97]
	v_mfma_f32_16x16x32_bf16 v[86:89], v[174:177], v[198:201], v[86:89]
	v_mfma_f32_16x16x32_bf16 v[78:81], v[166:169], v[206:209], v[78:81]
	v_mfma_f32_16x16x32_bf16 v[70:73], v[174:177], v[206:209], v[70:73]
	s_barrier
	s_add_i32 s40, 0, 0x14000
	s_add_i32 s7, s7, s3
	v_add_u32_e32 v145, s40, v153
	v_lshl_add_u64 v[218:219], s[0:1], 0, v[134:135]
	s_mov_b32 m0, s7
	ds_read_b128 v[210:213], v145
	ds_read_b128 v[214:217], v145 offset:1024
	ds_read_b128 v[238:241], v145 offset:2048
	ds_read_b128 v[242:245], v145 offset:3072
	global_load_lds_dwordx4 v[218:219], off
	v_lshl_add_u64 v[224:225], s[0:1], 0, v[130:131]
	s_add_i32 m0, s7, 0x2000
	s_nop 0
	global_load_lds_dwordx4 v[224:225], off
	s_barrier
	s_waitcnt lgkmcnt(0)
	s_waitcnt lgkmcnt(0)
	v_mfma_f32_16x16x32_bf16 v[122:125], v[210:213], v[178:181], v[122:125]
	v_mfma_f32_16x16x32_bf16 v[114:117], v[238:241], v[178:181], v[114:117]
	v_mfma_f32_16x16x32_bf16 v[106:109], v[210:213], v[186:189], v[106:109]
	v_mfma_f32_16x16x32_bf16 v[98:101], v[238:241], v[186:189], v[98:101]
	v_mfma_f32_16x16x32_bf16 v[90:93], v[210:213], v[194:197], v[90:93]
	v_mfma_f32_16x16x32_bf16 v[82:85], v[238:241], v[194:197], v[82:85]
	v_mfma_f32_16x16x32_bf16 v[74:77], v[210:213], v[202:205], v[74:77]
	v_mfma_f32_16x16x32_bf16 v[66:69], v[238:241], v[202:205], v[66:69]
	v_mfma_f32_16x16x32_bf16 v[122:125], v[214:217], v[182:185], v[122:125]
	v_mfma_f32_16x16x32_bf16 v[114:117], v[242:245], v[182:185], v[114:117]
	v_mfma_f32_16x16x32_bf16 v[106:109], v[214:217], v[190:193], v[106:109]
	v_mfma_f32_16x16x32_bf16 v[98:101], v[242:245], v[190:193], v[98:101]
	v_mfma_f32_16x16x32_bf16 v[90:93], v[214:217], v[198:201], v[90:93]
	v_mfma_f32_16x16x32_bf16 v[82:85], v[242:245], v[198:201], v[82:85]
	v_mfma_f32_16x16x32_bf16 v[74:77], v[214:217], v[206:209], v[74:77]
	v_mfma_f32_16x16x32_bf16 v[66:69], v[242:245], v[206:209], v[66:69]
	s_mov_b32 m0, s28
	v_lshl_add_u64 v[230:231], v[150:151], 0, v[136:137]
	s_barrier
	ds_read_b128 v[178:181], v157 offset:16384
	ds_read_b128 v[182:185], v157 offset:17408
	ds_read_b128 v[186:189], v157 offset:18432
	ds_read_b128 v[190:193], v157 offset:19456
	ds_read_b128 v[194:197], v157 offset:20480
	ds_read_b128 v[198:201], v157 offset:21504
	ds_read_b128 v[202:205], v157 offset:22528
	ds_read_b128 v[206:209], v157 offset:23552
	global_load_lds_dwordx4 v[230:231], off
	v_lshl_add_u64 v[246:247], v[150:151], 0, v[132:133]
	s_mov_b32 m0, s29
	s_nop 0
	global_load_lds_dwordx4 v[246:247], off
	s_barrier
	s_waitcnt lgkmcnt(0)
	s_waitcnt lgkmcnt(0)
	v_mfma_f32_16x16x32_bf16 v[58:61], v[162:165], v[178:181], v[58:61]
	v_mfma_f32_16x16x32_bf16 v[50:53], v[170:173], v[178:181], v[50:53]
	v_mfma_f32_16x16x32_bf16 v[42:45], v[162:165], v[186:189], v[42:45]
	v_mfma_f32_16x16x32_bf16 v[34:37], v[170:173], v[186:189], v[34:37]
	v_mfma_f32_16x16x32_bf16 v[26:29], v[162:165], v[194:197], v[26:29]
	v_mfma_f32_16x16x32_bf16 v[18:21], v[170:173], v[194:197], v[18:21]
	v_mfma_f32_16x16x32_bf16 v[6:9], v[162:165], v[202:205], v[6:9]
	v_mfma_f32_16x16x32_bf16 v[2:5], v[170:173], v[202:205], v[2:5]
	v_mfma_f32_16x16x32_bf16 v[58:61], v[166:169], v[182:185], v[58:61]
	v_mfma_f32_16x16x32_bf16 v[50:53], v[174:177], v[182:185], v[50:53]
	v_mfma_f32_16x16x32_bf16 v[42:45], v[166:169], v[190:193], v[42:45]
	v_mfma_f32_16x16x32_bf16 v[34:37], v[174:177], v[190:193], v[34:37]
	v_mfma_f32_16x16x32_bf16 v[26:29], v[166:169], v[198:201], v[26:29]
	v_mfma_f32_16x16x32_bf16 v[18:21], v[174:177], v[198:201], v[18:21]
	v_mfma_f32_16x16x32_bf16 v[6:9], v[166:169], v[206:209], v[6:9]
	v_mfma_f32_16x16x32_bf16 v[2:5], v[174:177], v[206:209], v[2:5]
	s_barrier
	s_add_u32 s0, s0, s94
	s_addc_u32 s1, s1, 0
	s_add_i32 s7, s40, s3
	v_lshl_add_u64 v[248:249], s[0:1], 0, v[134:135]
	s_mov_b32 m0, s7
	v_lshl_add_u64 v[232:233], s[0:1], 0, v[130:131]
	global_load_lds_dwordx4 v[248:249], off
	s_add_i32 m0, s7, 0x2000
	s_nop 0
	global_load_lds_dwordx4 v[232:233], off
	s_waitcnt vmcnt(6)
	s_barrier
	v_mfma_f32_16x16x32_bf16 v[62:65], v[210:213], v[178:181], v[62:65]
	v_mfma_f32_16x16x32_bf16 v[54:57], v[238:241], v[178:181], v[54:57]
	v_mfma_f32_16x16x32_bf16 v[46:49], v[210:213], v[186:189], v[46:49]
	v_mfma_f32_16x16x32_bf16 v[38:41], v[238:241], v[186:189], v[38:41]
	v_mfma_f32_16x16x32_bf16 v[30:33], v[210:213], v[194:197], v[30:33]
	v_mfma_f32_16x16x32_bf16 v[22:25], v[238:241], v[194:197], v[22:25]
	v_mfma_f32_16x16x32_bf16 v[14:17], v[210:213], v[202:205], v[14:17]
	v_mfma_f32_16x16x32_bf16 v[10:13], v[238:241], v[202:205], v[10:13]
	v_mfma_f32_16x16x32_bf16 v[62:65], v[214:217], v[182:185], v[62:65]
	v_mfma_f32_16x16x32_bf16 v[54:57], v[242:245], v[182:185], v[54:57]
	v_mfma_f32_16x16x32_bf16 v[46:49], v[214:217], v[190:193], v[46:49]
	v_mfma_f32_16x16x32_bf16 v[38:41], v[242:245], v[190:193], v[38:41]
	v_mfma_f32_16x16x32_bf16 v[30:33], v[214:217], v[198:201], v[30:33]
	v_mfma_f32_16x16x32_bf16 v[22:25], v[242:245], v[198:201], v[22:25]
	v_mfma_f32_16x16x32_bf16 v[14:17], v[214:217], v[206:209], v[14:17]
	v_mfma_f32_16x16x32_bf16 v[10:13], v[242:245], v[206:209], v[10:13]
	s_add_i32 s0, 0, 0x18000
	v_add_u32_e32 v145, s0, v153
	s_barrier
	ds_read_b128 v[162:165], v145
	ds_read_b128 v[166:169], v145 offset:1024
	ds_read_b128 v[170:173], v145 offset:2048
	ds_read_b128 v[174:177], v145 offset:3072
	v_lshl_add_u64 v[150:151], v[150:151], 0, s[94:95]
	s_mov_b32 m0, s34
	v_lshl_add_u64 v[210:211], v[150:151], 0, v[136:137]
	ds_read_b128 v[178:181], v157 offset:32768
	ds_read_b128 v[182:185], v157 offset:33792
	ds_read_b128 v[186:189], v157 offset:34816
	ds_read_b128 v[190:193], v157 offset:35840
	ds_read_b128 v[194:197], v157 offset:36864
	ds_read_b128 v[198:201], v157 offset:37888
	ds_read_b128 v[202:205], v157 offset:38912
	ds_read_b128 v[206:209], v157 offset:39936
	global_load_lds_dwordx4 v[210:211], off
	v_lshl_add_u64 v[150:151], v[150:151], 0, v[132:133]
	s_mov_b32 m0, s35
	s_nop 0
	global_load_lds_dwordx4 v[150:151], off
	s_waitcnt lgkmcnt(8)
	s_barrier
	s_waitcnt lgkmcnt(0)
	s_waitcnt lgkmcnt(0)
	v_mfma_f32_16x16x32_bf16 v[126:129], v[162:165], v[178:181], v[126:129]
	v_mfma_f32_16x16x32_bf16 v[118:121], v[170:173], v[178:181], v[118:121]
	v_mfma_f32_16x16x32_bf16 v[110:113], v[162:165], v[186:189], v[110:113]
	v_mfma_f32_16x16x32_bf16 v[102:105], v[170:173], v[186:189], v[102:105]
	v_mfma_f32_16x16x32_bf16 v[94:97], v[162:165], v[194:197], v[94:97]
	v_mfma_f32_16x16x32_bf16 v[86:89], v[170:173], v[194:197], v[86:89]
	v_mfma_f32_16x16x32_bf16 v[78:81], v[162:165], v[202:205], v[78:81]
	v_mfma_f32_16x16x32_bf16 v[70:73], v[170:173], v[202:205], v[70:73]
	v_mfma_f32_16x16x32_bf16 v[126:129], v[166:169], v[182:185], v[126:129]
	v_mfma_f32_16x16x32_bf16 v[118:121], v[174:177], v[182:185], v[118:121]
	v_mfma_f32_16x16x32_bf16 v[110:113], v[166:169], v[190:193], v[110:113]
	v_mfma_f32_16x16x32_bf16 v[102:105], v[174:177], v[190:193], v[102:105]
	v_mfma_f32_16x16x32_bf16 v[94:97], v[166:169], v[198:201], v[94:97]
	v_mfma_f32_16x16x32_bf16 v[86:89], v[174:177], v[198:201], v[86:89]
	v_mfma_f32_16x16x32_bf16 v[78:81], v[166:169], v[206:209], v[78:81]
	v_mfma_f32_16x16x32_bf16 v[70:73], v[174:177], v[206:209], v[70:73]
	s_barrier
	s_add_i32 s1, 0, 0x1c000
	s_add_i32 s0, s0, s3
	v_add_u32_e32 v145, s1, v153
	v_lshl_add_u64 v[150:151], v[218:219], 0, s[84:85]
	s_mov_b32 m0, s0
	ds_read_b128 v[210:213], v145
	ds_read_b128 v[214:217], v145 offset:1024
	ds_read_b128 v[238:241], v145 offset:2048
	ds_read_b128 v[242:245], v145 offset:3072
	global_load_lds_dwordx4 v[150:151], off
	v_lshl_add_u64 v[150:151], v[224:225], 0, s[84:85]
	s_add_i32 m0, s0, 0x2000
	s_nop 0
	global_load_lds_dwordx4 v[150:151], off
	s_barrier
	s_waitcnt lgkmcnt(0)
	s_waitcnt lgkmcnt(0)
	v_mfma_f32_16x16x32_bf16 v[122:125], v[210:213], v[178:181], v[122:125]
	v_mfma_f32_16x16x32_bf16 v[114:117], v[238:241], v[178:181], v[114:117]
	v_mfma_f32_16x16x32_bf16 v[106:109], v[210:213], v[186:189], v[106:109]
	v_mfma_f32_16x16x32_bf16 v[98:101], v[238:241], v[186:189], v[98:101]
	v_mfma_f32_16x16x32_bf16 v[90:93], v[210:213], v[194:197], v[90:93]
	v_mfma_f32_16x16x32_bf16 v[82:85], v[238:241], v[194:197], v[82:85]
	v_mfma_f32_16x16x32_bf16 v[74:77], v[210:213], v[202:205], v[74:77]
	v_mfma_f32_16x16x32_bf16 v[66:69], v[238:241], v[202:205], v[66:69]
	v_mfma_f32_16x16x32_bf16 v[122:125], v[214:217], v[182:185], v[122:125]
	v_mfma_f32_16x16x32_bf16 v[114:117], v[242:245], v[182:185], v[114:117]
	v_mfma_f32_16x16x32_bf16 v[106:109], v[214:217], v[190:193], v[106:109]
	v_mfma_f32_16x16x32_bf16 v[98:101], v[242:245], v[190:193], v[98:101]
	v_mfma_f32_16x16x32_bf16 v[90:93], v[214:217], v[198:201], v[90:93]
	v_mfma_f32_16x16x32_bf16 v[82:85], v[242:245], v[198:201], v[82:85]
	v_mfma_f32_16x16x32_bf16 v[74:77], v[214:217], v[206:209], v[74:77]
	v_mfma_f32_16x16x32_bf16 v[66:69], v[242:245], v[206:209], v[66:69]
	s_mov_b32 m0, s36
	v_lshl_add_u64 v[150:151], v[230:231], 0, s[84:85]
	s_barrier
	ds_read_b128 v[178:181], v157 offset:49152
	ds_read_b128 v[182:185], v157 offset:50176
	ds_read_b128 v[186:189], v157 offset:51200
	ds_read_b128 v[190:193], v157 offset:52224
	ds_read_b128 v[194:197], v157 offset:53248
	ds_read_b128 v[198:201], v157 offset:54272
	ds_read_b128 v[202:205], v157 offset:55296
	ds_read_b128 v[206:209], v157 offset:56320
	global_load_lds_dwordx4 v[150:151], off
	v_lshl_add_u64 v[150:151], v[246:247], 0, s[84:85]
	s_mov_b32 m0, s42
	s_nop 0
	global_load_lds_dwordx4 v[150:151], off
	s_barrier
	s_waitcnt lgkmcnt(0)
	s_waitcnt lgkmcnt(0)
	v_mfma_f32_16x16x32_bf16 v[58:61], v[162:165], v[178:181], v[58:61]
	v_mfma_f32_16x16x32_bf16 v[50:53], v[170:173], v[178:181], v[50:53]
	v_mfma_f32_16x16x32_bf16 v[42:45], v[162:165], v[186:189], v[42:45]
	v_mfma_f32_16x16x32_bf16 v[34:37], v[170:173], v[186:189], v[34:37]
	v_mfma_f32_16x16x32_bf16 v[26:29], v[162:165], v[194:197], v[26:29]
	v_mfma_f32_16x16x32_bf16 v[18:21], v[170:173], v[194:197], v[18:21]
	v_mfma_f32_16x16x32_bf16 v[6:9], v[162:165], v[202:205], v[6:9]
	v_mfma_f32_16x16x32_bf16 v[2:5], v[170:173], v[202:205], v[2:5]
	v_mfma_f32_16x16x32_bf16 v[58:61], v[166:169], v[182:185], v[58:61]
	v_mfma_f32_16x16x32_bf16 v[50:53], v[174:177], v[182:185], v[50:53]
	v_mfma_f32_16x16x32_bf16 v[42:45], v[166:169], v[190:193], v[42:45]
	v_mfma_f32_16x16x32_bf16 v[34:37], v[174:177], v[190:193], v[34:37]
	v_mfma_f32_16x16x32_bf16 v[26:29], v[166:169], v[198:201], v[26:29]
	v_mfma_f32_16x16x32_bf16 v[18:21], v[174:177], v[198:201], v[18:21]
	v_mfma_f32_16x16x32_bf16 v[6:9], v[166:169], v[206:209], v[6:9]
	v_mfma_f32_16x16x32_bf16 v[2:5], v[174:177], v[206:209], v[2:5]
	s_barrier
	s_add_i32 s0, s1, s3
	v_lshl_add_u64 v[150:151], v[248:249], 0, s[84:85]
	s_mov_b32 m0, s0
	s_nop 0
	global_load_lds_dwordx4 v[150:151], off
	v_lshl_add_u64 v[150:151], v[232:233], 0, s[84:85]
	s_add_i32 m0, s0, 0x2000
	s_nop 0
	global_load_lds_dwordx4 v[150:151], off
	s_waitcnt vmcnt(6)
	s_barrier
	v_mfma_f32_16x16x32_bf16 v[62:65], v[210:213], v[178:181], v[62:65]
	v_mfma_f32_16x16x32_bf16 v[54:57], v[238:241], v[178:181], v[54:57]
	v_mfma_f32_16x16x32_bf16 v[46:49], v[210:213], v[186:189], v[46:49]
	v_mfma_f32_16x16x32_bf16 v[38:41], v[238:241], v[186:189], v[38:41]
	v_mfma_f32_16x16x32_bf16 v[30:33], v[210:213], v[194:197], v[30:33]
	v_mfma_f32_16x16x32_bf16 v[22:25], v[238:241], v[194:197], v[22:25]
	v_mfma_f32_16x16x32_bf16 v[14:17], v[210:213], v[202:205], v[14:17]
	v_mfma_f32_16x16x32_bf16 v[10:13], v[238:241], v[202:205], v[10:13]
	v_mfma_f32_16x16x32_bf16 v[62:65], v[214:217], v[182:185], v[62:65]
	v_mfma_f32_16x16x32_bf16 v[54:57], v[242:245], v[182:185], v[54:57]
	v_mfma_f32_16x16x32_bf16 v[46:49], v[214:217], v[190:193], v[46:49]
	v_mfma_f32_16x16x32_bf16 v[38:41], v[242:245], v[190:193], v[38:41]
	v_mfma_f32_16x16x32_bf16 v[30:33], v[214:217], v[198:201], v[30:33]
	v_mfma_f32_16x16x32_bf16 v[22:25], v[242:245], v[198:201], v[22:25]
	v_mfma_f32_16x16x32_bf16 v[14:17], v[214:217], v[206:209], v[14:17]
	v_mfma_f32_16x16x32_bf16 v[10:13], v[242:245], v[206:209], v[10:13]
	s_add_u32 s4, s4, 0x100
	s_addc_u32 s5, s5, 0
	v_lshl_add_u64 v[148:149], v[148:149], 0, s[86:87]
	s_cmp_ge_u32 s6, s13
	s_mov_b32 s0, s6
	s_barrier
	s_cbranch_scc0 .LBB0_824
	v_cmp_lt_i32_e32 vcc, v227, v222
	ds_read2st64_b32 v[150:151], v161 offset1:1
	ds_read2st64_b32 v[168:169], v161 offset0:2 offset1:3
	ds_read2st64_b32 v[170:171], v161 offset0:4 offset1:5
	ds_read2st64_b32 v[148:149], v161 offset0:6 offset1:7
	v_cndmask_b32_e32 v145, v221, v227, vcc
	v_cmp_lt_i32_e32 vcc, v228, v222
	v_lshlrev_b32_e32 v145, 2, v145
	v_cndmask_b32_e32 v224, v221, v228, vcc
	s_mov_b32 s0, 0x358637bd
	v_lshlrev_b32_e32 v224, 2, v224
	s_mov_b32 s4, 0x3a800000
	v_mov_b32_e32 v180, s0
	v_lshl_or_b32 v164, s17, 7, v155
	s_mov_b32 s17, s90
	s_mov_b32 s40, s91
	s_waitcnt lgkmcnt(0)
	ds_bpermute_b32 v172, v145, v150
	ds_bpermute_b32 v173, v145, v151
	ds_bpermute_b32 v174, v145, v168
	ds_bpermute_b32 v175, v145, v169
	ds_bpermute_b32 v176, v145, v170
	ds_bpermute_b32 v177, v145, v171
	ds_bpermute_b32 v178, v145, v148
	ds_bpermute_b32 v179, v145, v149
	v_ashrrev_i32_e32 v165, 31, v164
	v_mov_b64_e32 v[212:213], s[20:21]
	v_lshlrev_b64 v[216:217], 1, v[164:165]
	v_mad_i64_i32 v[212:213], vcc, v144, s89, v[212:213]
	s_waitcnt lgkmcnt(0)
	v_pk_add_f32 v[150:151], v[150:151], v[172:173]
	v_pk_add_f32 v[168:169], v[168:169], v[174:175]
	v_pk_add_f32 v[170:171], v[170:171], v[176:177]
	v_pk_add_f32 v[148:149], v[148:149], v[178:179]
	s_waitcnt lgkmcnt(0)
	ds_bpermute_b32 v172, v224, v150
	ds_bpermute_b32 v173, v224, v151
	ds_bpermute_b32 v174, v224, v168
	ds_bpermute_b32 v175, v224, v169
	ds_bpermute_b32 v176, v224, v170
	ds_bpermute_b32 v177, v224, v171
	ds_bpermute_b32 v178, v224, v148
	ds_bpermute_b32 v179, v224, v149
	v_mov_b64_e32 v[218:219], 0
	v_lshl_add_u64 v[212:213], v[212:213], 0, v[216:217]
	s_waitcnt lgkmcnt(0)
	v_pk_add_f32 v[150:151], v[150:151], v[172:173]
	v_pk_add_f32 v[168:169], v[168:169], v[174:175]
	v_pk_add_f32 v[170:171], v[170:171], v[176:177]
	v_pk_add_f32 v[148:149], v[148:149], v[178:179]
	v_pk_fma_f32 v[150:151], v[150:151], s[4:5], v[180:181] op_sel_hi:[1,0,0]
	v_pk_fma_f32 v[168:169], v[168:169], s[4:5], v[180:181] op_sel_hi:[1,0,0]
	v_pk_fma_f32 v[170:171], v[170:171], s[4:5], v[180:181] op_sel_hi:[1,0,0]
	v_pk_fma_f32 v[148:149], v[148:149], s[4:5], v[180:181] op_sel_hi:[1,0,0]
	s_mov_b32 s0, 0xbfb8aa3b
	v_rsq_f32_e32 v150, v150
	v_rsq_f32_e32 v151, v151
	v_rsq_f32_e32 v168, v168
	v_rsq_f32_e32 v169, v169
	v_rsq_f32_e32 v170, v170
	v_rsq_f32_e32 v171, v171
	v_rsq_f32_e32 v148, v148
	v_rsq_f32_e32 v149, v149
	v_pk_mul_f32 v[126:127], v[126:127], v[150:151] op_sel_hi:[1,0]
	v_pk_mul_f32 v[128:129], v[128:129], v[150:151] op_sel_hi:[1,0]
	v_pk_mul_f32 v[118:119], v[118:119], v[150:151] op_sel_hi:[1,0]
	v_pk_mul_f32 v[120:121], v[120:121], v[150:151] op_sel_hi:[1,0]
	v_pk_mul_f32 v[172:173], v[126:127], s[0:1] op_sel_hi:[1,0]
	v_pk_mul_f32 v[174:175], v[128:129], s[0:1] op_sel_hi:[1,0]
	v_pk_mul_f32 v[176:177], v[118:119], s[0:1] op_sel_hi:[1,0]
	v_pk_mul_f32 v[178:179], v[120:121], s[0:1] op_sel_hi:[1,0]
	v_pk_mul_f32 v[122:123], v[122:123], v[150:151] op_sel_hi:[1,0]
	v_pk_mul_f32 v[124:125], v[124:125], v[150:151] op_sel_hi:[1,0]
	v_pk_mul_f32 v[114:115], v[114:115], v[150:151] op_sel_hi:[1,0]
	v_pk_mul_f32 v[116:117], v[116:117], v[150:151] op_sel_hi:[1,0]
	v_exp_f32_e32 v172, v172
	v_pk_mul_f32 v[110:111], v[110:111], v[150:151] op_sel:[0,1] op_sel_hi:[1,1]
	v_pk_mul_f32 v[112:113], v[112:113], v[150:151] op_sel:[0,1] op_sel_hi:[1,1]
	v_exp_f32_e32 v173, v173
	v_pk_mul_f32 v[102:103], v[102:103], v[150:151] op_sel:[0,1] op_sel_hi:[1,1]
	v_exp_f32_e32 v174, v174
	v_pk_mul_f32 v[104:105], v[104:105], v[150:151] op_sel:[0,1] op_sel_hi:[1,1]
	v_pk_mul_f32 v[180:181], v[110:111], s[0:1] op_sel_hi:[1,0]
	v_exp_f32_e32 v175, v175
	v_pk_mul_f32 v[182:183], v[112:113], s[0:1] op_sel_hi:[1,0]
	v_exp_f32_e32 v176, v176
	v_pk_mul_f32 v[184:185], v[102:103], s[0:1] op_sel_hi:[1,0]
	v_pk_mul_f32 v[186:187], v[104:105], s[0:1] op_sel_hi:[1,0]
	v_exp_f32_e32 v177, v177
	v_pk_mul_f32 v[106:107], v[106:107], v[150:151] op_sel:[0,1] op_sel_hi:[1,1]
	v_exp_f32_e32 v178, v178
	v_pk_mul_f32 v[108:109], v[108:109], v[150:151] op_sel:[0,1] op_sel_hi:[1,1]
	v_pk_mul_f32 v[98:99], v[98:99], v[150:151] op_sel:[0,1] op_sel_hi:[1,1]
	v_exp_f32_e32 v179, v179
	v_pk_mul_f32 v[100:101], v[100:101], v[150:151] op_sel:[0,1] op_sel_hi:[1,1]
	v_exp_f32_e32 v180, v180
	v_pk_mul_f32 v[94:95], v[94:95], v[168:169] op_sel_hi:[1,0]
	v_pk_mul_f32 v[96:97], v[96:97], v[168:169] op_sel_hi:[1,0]
	v_exp_f32_e32 v181, v181
	v_pk_mul_f32 v[86:87], v[86:87], v[168:169] op_sel_hi:[1,0]
	v_pk_mul_f32 v[88:89], v[88:89], v[168:169] op_sel_hi:[1,0]
	v_exp_f32_e32 v182, v182
	v_pk_mul_f32 v[188:189], v[94:95], s[0:1] op_sel_hi:[1,0]
	v_pk_mul_f32 v[190:191], v[96:97], s[0:1] op_sel_hi:[1,0]
	v_exp_f32_e32 v183, v183
	v_pk_mul_f32 v[192:193], v[86:87], s[0:1] op_sel_hi:[1,0]
	v_pk_mul_f32 v[194:195], v[88:89], s[0:1] op_sel_hi:[1,0]
	v_exp_f32_e32 v184, v184
	v_pk_mul_f32 v[90:91], v[90:91], v[168:169] op_sel_hi:[1,0]
	v_pk_mul_f32 v[92:93], v[92:93], v[168:169] op_sel_hi:[1,0]
	v_exp_f32_e32 v185, v185
	v_pk_mul_f32 v[82:83], v[82:83], v[168:169] op_sel_hi:[1,0]
	v_pk_mul_f32 v[84:85], v[84:85], v[168:169] op_sel_hi:[1,0]
	v_exp_f32_e32 v186, v186
	v_pk_add_f32 v[172:173], v[172:173], 1.0 op_sel_hi:[1,0]
	v_pk_add_f32 v[174:175], v[174:175], 1.0 op_sel_hi:[1,0]
	v_exp_f32_e32 v187, v187
	v_pk_add_f32 v[176:177], v[176:177], 1.0 op_sel_hi:[1,0]
	v_pk_add_f32 v[178:179], v[178:179], 1.0 op_sel_hi:[1,0]
	v_exp_f32_e32 v188, v188
	v_pk_mul_f32 v[78:79], v[78:79], v[168:169] op_sel:[0,1] op_sel_hi:[1,1]
	v_rcp_f32_e32 v172, v172
	v_pk_mul_f32 v[80:81], v[80:81], v[168:169] op_sel:[0,1] op_sel_hi:[1,1]
	v_exp_f32_e32 v189, v189
	v_pk_mul_f32 v[70:71], v[70:71], v[168:169] op_sel:[0,1] op_sel_hi:[1,1]
	v_rcp_f32_e32 v173, v173
	v_pk_mul_f32 v[72:73], v[72:73], v[168:169] op_sel:[0,1] op_sel_hi:[1,1]
	v_exp_f32_e32 v190, v190
	v_pk_mul_f32 v[196:197], v[78:79], s[0:1] op_sel_hi:[1,0]
	v_rcp_f32_e32 v174, v174
	v_pk_mul_f32 v[198:199], v[80:81], s[0:1] op_sel_hi:[1,0]
	v_exp_f32_e32 v191, v191
	v_pk_mul_f32 v[200:201], v[70:71], s[0:1] op_sel_hi:[1,0]
	v_rcp_f32_e32 v175, v175
	v_pk_mul_f32 v[202:203], v[72:73], s[0:1] op_sel_hi:[1,0]
	v_exp_f32_e32 v192, v192
	v_pk_mul_f32 v[74:75], v[74:75], v[168:169] op_sel:[0,1] op_sel_hi:[1,1]
	v_rcp_f32_e32 v176, v176
	v_pk_mul_f32 v[76:77], v[76:77], v[168:169] op_sel:[0,1] op_sel_hi:[1,1]
	v_exp_f32_e32 v193, v193
	v_pk_mul_f32 v[66:67], v[66:67], v[168:169] op_sel:[0,1] op_sel_hi:[1,1]
	v_rcp_f32_e32 v177, v177
	v_pk_mul_f32 v[68:69], v[68:69], v[168:169] op_sel:[0,1] op_sel_hi:[1,1]
	v_exp_f32_e32 v194, v194
	v_pk_add_f32 v[180:181], v[180:181], 1.0 op_sel_hi:[1,0]
	v_rcp_f32_e32 v178, v178
	v_pk_add_f32 v[182:183], v[182:183], 1.0 op_sel_hi:[1,0]
	v_exp_f32_e32 v195, v195
	v_pk_add_f32 v[184:185], v[184:185], 1.0 op_sel_hi:[1,0]
	v_rcp_f32_e32 v179, v179
	v_pk_add_f32 v[186:187], v[186:187], 1.0 op_sel_hi:[1,0]
	v_exp_f32_e32 v196, v196
	v_pk_mul_f32 v[58:59], v[58:59], v[170:171] op_sel_hi:[1,0]
	v_pk_mul_f32 v[60:61], v[60:61], v[170:171] op_sel_hi:[1,0]
	v_rcp_f32_e32 v180, v180
	v_pk_mul_f32 v[50:51], v[50:51], v[170:171] op_sel_hi:[1,0]
	v_pk_mul_f32 v[52:53], v[52:53], v[170:171] op_sel_hi:[1,0]
	v_exp_f32_e32 v197, v197
	v_pk_mul_f32 v[204:205], v[58:59], s[0:1] op_sel_hi:[1,0]
	v_pk_mul_f32 v[206:207], v[60:61], s[0:1] op_sel_hi:[1,0]
	v_rcp_f32_e32 v181, v181
	v_pk_mul_f32 v[208:209], v[50:51], s[0:1] op_sel_hi:[1,0]
	v_pk_mul_f32 v[210:211], v[52:53], s[0:1] op_sel_hi:[1,0]
	v_exp_f32_e32 v198, v198
	v_pk_mul_f32 v[62:63], v[62:63], v[170:171] op_sel_hi:[1,0]
	v_pk_mul_f32 v[64:65], v[64:65], v[170:171] op_sel_hi:[1,0]
	v_rcp_f32_e32 v182, v182
	v_pk_mul_f32 v[54:55], v[54:55], v[170:171] op_sel_hi:[1,0]
	v_exp_f32_e32 v199, v199
	v_pk_mul_f32 v[56:57], v[56:57], v[170:171] op_sel_hi:[1,0]
	v_pk_add_f32 v[188:189], v[188:189], 1.0 op_sel_hi:[1,0]
	v_rcp_f32_e32 v183, v183
	v_pk_add_f32 v[190:191], v[190:191], 1.0 op_sel_hi:[1,0]
	v_pk_add_f32 v[192:193], v[192:193], 1.0 op_sel_hi:[1,0]
	v_exp_f32_e32 v200, v200
	v_pk_add_f32 v[194:195], v[194:195], 1.0 op_sel_hi:[1,0]
	v_pk_mul_f32 v[126:127], v[126:127], v[172:173]
	v_rcp_f32_e32 v184, v184
	v_pk_mul_f32 v[128:129], v[128:129], v[174:175]
	v_pk_mul_f32 v[118:119], v[118:119], v[176:177]
	v_exp_f32_e32 v201, v201
	v_pk_mul_f32 v[120:121], v[120:121], v[178:179]
	v_rcp_f32_e32 v185, v185
	v_pk_mul_f32 v[122:123], v[122:123], v[126:127]
	v_pk_mul_f32 v[124:125], v[124:125], v[128:129]
	v_exp_f32_e32 v202, v202
	v_pk_mul_f32 v[114:115], v[114:115], v[118:119]
	v_pk_mul_f32 v[116:117], v[116:117], v[120:121]
	v_rcp_f32_e32 v186, v186
	v_cvt_pk_bf16_f32 v122, v122, v123
	v_cvt_pk_bf16_f32 v123, v124, v125
	v_exp_f32_e32 v203, v203
	v_cvt_pk_bf16_f32 v124, v114, v115
	v_cvt_pk_bf16_f32 v125, v116, v117
	v_rcp_f32_e32 v187, v187
	global_store_dwordx4 v[212:213], v[122:125], off
	v_exp_f32_e32 v204, v204
	v_pk_mul_f32 v[42:43], v[42:43], v[170:171] op_sel:[0,1] op_sel_hi:[1,1]
	v_pk_mul_f32 v[44:45], v[44:45], v[170:171] op_sel:[0,1] op_sel_hi:[1,1]
	v_rcp_f32_e32 v188, v188
	v_pk_mul_f32 v[34:35], v[34:35], v[170:171] op_sel:[0,1] op_sel_hi:[1,1]
	v_pk_mul_f32 v[36:37], v[36:37], v[170:171] op_sel:[0,1] op_sel_hi:[1,1]
	v_exp_f32_e32 v205, v205
	v_pk_mul_f32 v[172:173], v[42:43], s[0:1] op_sel_hi:[1,0]
	v_pk_mul_f32 v[174:175], v[44:45], s[0:1] op_sel_hi:[1,0]
	v_rcp_f32_e32 v189, v189
	v_pk_mul_f32 v[176:177], v[34:35], s[0:1] op_sel_hi:[1,0]
	v_pk_mul_f32 v[178:179], v[36:37], s[0:1] op_sel_hi:[1,0]
	v_exp_f32_e32 v206, v206
	v_pk_mul_f32 v[46:47], v[46:47], v[170:171] op_sel:[0,1] op_sel_hi:[1,1]
	v_pk_mul_f32 v[48:49], v[48:49], v[170:171] op_sel:[0,1] op_sel_hi:[1,1]
	v_rcp_f32_e32 v190, v190
	v_pk_mul_f32 v[38:39], v[38:39], v[170:171] op_sel:[0,1] op_sel_hi:[1,1]
	v_pk_mul_f32 v[40:41], v[40:41], v[170:171] op_sel:[0,1] op_sel_hi:[1,1]
	v_exp_f32_e32 v207, v207
	v_pk_add_f32 v[196:197], v[196:197], 1.0 op_sel_hi:[1,0]
	v_pk_add_f32 v[198:199], v[198:199], 1.0 op_sel_hi:[1,0]
	v_rcp_f32_e32 v191, v191
	v_pk_add_f32 v[200:201], v[200:201], 1.0 op_sel_hi:[1,0]
	v_pk_add_f32 v[202:203], v[202:203], 1.0 op_sel_hi:[1,0]
	v_exp_f32_e32 v208, v208
	v_pk_mul_f32 v[110:111], v[110:111], v[180:181]
	v_pk_mul_f32 v[112:113], v[112:113], v[182:183]
	v_rcp_f32_e32 v192, v192
	v_pk_mul_f32 v[102:103], v[102:103], v[184:185]
	v_pk_mul_f32 v[104:105], v[104:105], v[186:187]
	v_exp_f32_e32 v209, v209
	s_mov_b32 s4, 0x16000
	s_mov_b32 s5, 0
	v_rcp_f32_e32 v193, v193
	v_pk_mul_f32 v[106:107], v[106:107], v[110:111]
	v_pk_mul_f32 v[108:109], v[108:109], v[112:113]
	v_exp_f32_e32 v210, v210
	v_lshl_add_u64 v[214:215], v[212:213], 0, s[4:5]
	v_pk_mul_f32 v[98:99], v[98:99], v[102:103]
	v_rcp_f32_e32 v194, v194
	v_pk_mul_f32 v[100:101], v[100:101], v[104:105]
	v_cvt_pk_bf16_f32 v106, v106, v107
	v_exp_f32_e32 v211, v211
	v_cvt_pk_bf16_f32 v107, v108, v109
	v_cvt_pk_bf16_f32 v108, v98, v99
	v_rcp_f32_e32 v195, v195
	v_cvt_pk_bf16_f32 v109, v100, v101
	global_store_dwordx4 v[214:215], v[106:109], off
	v_exp_f32_e32 v172, v172
	v_pk_mul_f32 v[26:27], v[26:27], v[148:149] op_sel_hi:[1,0]
	v_pk_mul_f32 v[28:29], v[28:29], v[148:149] op_sel_hi:[1,0]
	v_rcp_f32_e32 v196, v196
	v_pk_mul_f32 v[18:19], v[18:19], v[148:149] op_sel_hi:[1,0]
	v_pk_mul_f32 v[20:21], v[20:21], v[148:149] op_sel_hi:[1,0]
	v_exp_f32_e32 v173, v173
	v_pk_mul_f32 v[180:181], v[26:27], s[0:1] op_sel_hi:[1,0]
	v_pk_mul_f32 v[182:183], v[28:29], s[0:1] op_sel_hi:[1,0]
	v_rcp_f32_e32 v197, v197
	v_pk_mul_f32 v[184:185], v[18:19], s[0:1] op_sel_hi:[1,0]
	v_pk_mul_f32 v[186:187], v[20:21], s[0:1] op_sel_hi:[1,0]
	v_exp_f32_e32 v174, v174
	v_pk_mul_f32 v[30:31], v[30:31], v[148:149] op_sel_hi:[1,0]
	v_pk_mul_f32 v[32:33], v[32:33], v[148:149] op_sel_hi:[1,0]
	v_rcp_f32_e32 v198, v198
	v_pk_mul_f32 v[22:23], v[22:23], v[148:149] op_sel_hi:[1,0]
	v_pk_mul_f32 v[24:25], v[24:25], v[148:149] op_sel_hi:[1,0]
	v_exp_f32_e32 v175, v175
	v_pk_add_f32 v[204:205], v[204:205], 1.0 op_sel_hi:[1,0]
	v_pk_add_f32 v[206:207], v[206:207], 1.0 op_sel_hi:[1,0]
	v_rcp_f32_e32 v199, v199
	v_pk_add_f32 v[208:209], v[208:209], 1.0 op_sel_hi:[1,0]
	v_pk_add_f32 v[210:211], v[210:211], 1.0 op_sel_hi:[1,0]
	v_exp_f32_e32 v176, v176
	v_pk_mul_f32 v[94:95], v[94:95], v[188:189]
	v_pk_mul_f32 v[96:97], v[96:97], v[190:191]
	v_rcp_f32_e32 v200, v200
	v_pk_mul_f32 v[86:87], v[86:87], v[192:193]
	v_pk_mul_f32 v[88:89], v[88:89], v[194:195]
	v_exp_f32_e32 v177, v177
	s_mov_b32 s4, 0x16000
	s_mov_b32 s5, 0
	v_rcp_f32_e32 v201, v201
	v_pk_mul_f32 v[90:91], v[90:91], v[94:95]
	v_pk_mul_f32 v[92:93], v[92:93], v[96:97]
	v_exp_f32_e32 v178, v178
	v_lshl_add_u64 v[212:213], v[214:215], 0, s[4:5]
	v_pk_mul_f32 v[82:83], v[82:83], v[86:87]
	v_rcp_f32_e32 v202, v202
	v_pk_mul_f32 v[84:85], v[84:85], v[88:89]
	v_cvt_pk_bf16_f32 v90, v90, v91
	v_exp_f32_e32 v179, v179
	v_cvt_pk_bf16_f32 v91, v92, v93
	v_cvt_pk_bf16_f32 v92, v82, v83
	v_rcp_f32_e32 v203, v203
	v_cvt_pk_bf16_f32 v93, v84, v85
	global_store_dwordx4 v[212:213], v[90:93], off
	v_exp_f32_e32 v180, v180
	v_pk_mul_f32 v[6:7], v[6:7], v[148:149] op_sel:[0,1] op_sel_hi:[1,1]
	v_pk_mul_f32 v[8:9], v[8:9], v[148:149] op_sel:[0,1] op_sel_hi:[1,1]
	v_rcp_f32_e32 v204, v204
	v_pk_mul_f32 v[2:3], v[2:3], v[148:149] op_sel:[0,1] op_sel_hi:[1,1]
	v_pk_mul_f32 v[4:5], v[4:5], v[148:149] op_sel:[0,1] op_sel_hi:[1,1]
	v_exp_f32_e32 v181, v181
	v_pk_mul_f32 v[188:189], v[6:7], s[0:1] op_sel_hi:[1,0]
	v_pk_mul_f32 v[190:191], v[8:9], s[0:1] op_sel_hi:[1,0]
	v_rcp_f32_e32 v205, v205
	v_pk_mul_f32 v[192:193], v[2:3], s[0:1] op_sel_hi:[1,0]
	v_pk_mul_f32 v[194:195], v[4:5], s[0:1] op_sel_hi:[1,0]
	v_exp_f32_e32 v182, v182
	v_pk_mul_f32 v[14:15], v[14:15], v[148:149] op_sel:[0,1] op_sel_hi:[1,1]
	v_pk_mul_f32 v[16:17], v[16:17], v[148:149] op_sel:[0,1] op_sel_hi:[1,1]
	v_rcp_f32_e32 v206, v206
	v_pk_mul_f32 v[10:11], v[10:11], v[148:149] op_sel:[0,1] op_sel_hi:[1,1]
	v_pk_mul_f32 v[12:13], v[12:13], v[148:149] op_sel:[0,1] op_sel_hi:[1,1]
	v_exp_f32_e32 v183, v183
	v_pk_add_f32 v[172:173], v[172:173], 1.0 op_sel_hi:[1,0]
	v_pk_add_f32 v[174:175], v[174:175], 1.0 op_sel_hi:[1,0]
	v_rcp_f32_e32 v207, v207
	v_pk_add_f32 v[176:177], v[176:177], 1.0 op_sel_hi:[1,0]
	v_pk_add_f32 v[178:179], v[178:179], 1.0 op_sel_hi:[1,0]
	v_exp_f32_e32 v184, v184
	v_pk_mul_f32 v[78:79], v[78:79], v[196:197]
	v_pk_mul_f32 v[80:81], v[80:81], v[198:199]
	v_rcp_f32_e32 v208, v208
	v_pk_mul_f32 v[70:71], v[70:71], v[200:201]
	v_pk_mul_f32 v[72:73], v[72:73], v[202:203]
	v_exp_f32_e32 v185, v185
	s_mov_b32 s4, 0x16000
	s_mov_b32 s5, 0
	v_rcp_f32_e32 v209, v209
	v_pk_mul_f32 v[74:75], v[74:75], v[78:79]
	v_pk_mul_f32 v[76:77], v[76:77], v[80:81]
	v_exp_f32_e32 v186, v186
	v_lshl_add_u64 v[214:215], v[212:213], 0, s[4:5]
	v_pk_mul_f32 v[66:67], v[66:67], v[70:71]
	v_rcp_f32_e32 v210, v210
	v_pk_mul_f32 v[68:69], v[68:69], v[72:73]
	v_cvt_pk_bf16_f32 v74, v74, v75
	v_exp_f32_e32 v187, v187
	v_cvt_pk_bf16_f32 v75, v76, v77
	v_cvt_pk_bf16_f32 v76, v66, v67
	v_rcp_f32_e32 v211, v211
	v_cvt_pk_bf16_f32 v77, v68, v69
	global_store_dwordx4 v[214:215], v[74:77], off
	v_exp_f32_e32 v188, v188
	v_pk_add_f32 v[180:181], v[180:181], 1.0 op_sel_hi:[1,0]
	v_pk_add_f32 v[182:183], v[182:183], 1.0 op_sel_hi:[1,0]
	v_rcp_f32_e32 v172, v172
	v_pk_add_f32 v[184:185], v[184:185], 1.0 op_sel_hi:[1,0]
	v_exp_f32_e32 v189, v189
	v_pk_add_f32 v[186:187], v[186:187], 1.0 op_sel_hi:[1,0]
	v_rcp_f32_e32 v173, v173
	v_pk_mul_f32 v[58:59], v[58:59], v[204:205]
	v_exp_f32_e32 v190, v190
	v_pk_mul_f32 v[60:61], v[60:61], v[206:207]
	v_pk_mul_f32 v[50:51], v[50:51], v[208:209]
	v_rcp_f32_e32 v174, v174
	v_pk_mul_f32 v[52:53], v[52:53], v[210:211]
	v_exp_f32_e32 v191, v191
	s_mov_b32 s4, 0x6e000
	v_rcp_f32_e32 v175, v175
	s_mov_b32 s5, 0
	v_exp_f32_e32 v192, v192
	v_pk_mul_f32 v[62:63], v[62:63], v[58:59]
	v_pk_mul_f32 v[64:65], v[64:65], v[60:61]
	v_rcp_f32_e32 v176, v176
	v_lshl_add_u64 v[212:213], v[214:215], 0, s[4:5]
	v_exp_f32_e32 v193, v193
	v_pk_mul_f32 v[54:55], v[54:55], v[50:51]
	v_rcp_f32_e32 v177, v177
	v_pk_mul_f32 v[56:57], v[56:57], v[52:53]
	v_exp_f32_e32 v194, v194
	v_cvt_pk_bf16_f32 v62, v62, v63
	v_cvt_pk_bf16_f32 v63, v64, v65
	v_rcp_f32_e32 v178, v178
	v_cvt_pk_bf16_f32 v64, v54, v55
	v_exp_f32_e32 v195, v195
	v_cvt_pk_bf16_f32 v65, v56, v57
	v_rcp_f32_e32 v179, v179
	global_store_dwordx4 v[212:213], v[62:65], off
	v_rcp_f32_e32 v180, v180
	v_pk_add_f32 v[188:189], v[188:189], 1.0 op_sel_hi:[1,0]
	v_pk_add_f32 v[190:191], v[190:191], 1.0 op_sel_hi:[1,0]
	v_pk_add_f32 v[192:193], v[192:193], 1.0 op_sel_hi:[1,0]
	v_rcp_f32_e32 v181, v181
	v_pk_add_f32 v[194:195], v[194:195], 1.0 op_sel_hi:[1,0]
	v_pk_mul_f32 v[42:43], v[42:43], v[172:173]
	v_rcp_f32_e32 v182, v182
	v_pk_mul_f32 v[44:45], v[44:45], v[174:175]
	v_pk_mul_f32 v[34:35], v[34:35], v[176:177]
	v_pk_mul_f32 v[36:37], v[36:37], v[178:179]
	v_rcp_f32_e32 v183, v183
	s_mov_b32 s4, 0x16000
	s_mov_b32 s5, 0
	v_rcp_f32_e32 v184, v184
	v_pk_mul_f32 v[46:47], v[46:47], v[42:43]
	v_pk_mul_f32 v[48:49], v[48:49], v[44:45]
	v_lshl_add_u64 v[214:215], v[212:213], 0, s[4:5]
	v_rcp_f32_e32 v185, v185
	v_pk_mul_f32 v[38:39], v[38:39], v[34:35]
	v_pk_mul_f32 v[40:41], v[40:41], v[36:37]
	v_rcp_f32_e32 v186, v186
	v_cvt_pk_bf16_f32 v46, v46, v47
	v_cvt_pk_bf16_f32 v47, v48, v49
	v_cvt_pk_bf16_f32 v48, v38, v39
	v_rcp_f32_e32 v187, v187
	v_cvt_pk_bf16_f32 v49, v40, v41
	global_store_dwordx4 v[214:215], v[46:49], off
	v_rcp_f32_e32 v188, v188
	v_pk_mul_f32 v[26:27], v[26:27], v[180:181]
	v_pk_mul_f32 v[28:29], v[28:29], v[182:183]
	v_rcp_f32_e32 v189, v189
	v_pk_mul_f32 v[18:19], v[18:19], v[184:185]
	v_pk_mul_f32 v[20:21], v[20:21], v[186:187]
	v_rcp_f32_e32 v190, v190
	s_mov_b32 s4, 0x16000
	s_mov_b32 s5, 0
	v_rcp_f32_e32 v191, v191
	v_pk_mul_f32 v[30:31], v[30:31], v[26:27]
	v_pk_mul_f32 v[32:33], v[32:33], v[28:29]
	v_rcp_f32_e32 v192, v192
	v_lshl_add_u64 v[212:213], v[214:215], 0, s[4:5]
	v_pk_mul_f32 v[22:23], v[22:23], v[18:19]
	v_rcp_f32_e32 v193, v193
	v_pk_mul_f32 v[24:25], v[24:25], v[20:21]
	v_cvt_pk_bf16_f32 v30, v30, v31
	v_rcp_f32_e32 v194, v194
	v_cvt_pk_bf16_f32 v31, v32, v33
	v_cvt_pk_bf16_f32 v32, v22, v23
	v_rcp_f32_e32 v195, v195
	v_cvt_pk_bf16_f32 v33, v24, v25
	global_store_dwordx4 v[212:213], v[30:33], off
	v_pk_mul_f32 v[6:7], v[6:7], v[188:189]
	v_pk_mul_f32 v[8:9], v[8:9], v[190:191]
	v_pk_mul_f32 v[2:3], v[2:3], v[192:193]
	v_pk_mul_f32 v[4:5], v[4:5], v[194:195]
	s_mov_b32 s4, 0x16000
	s_mov_b32 s5, 0
	v_pk_mul_f32 v[14:15], v[14:15], v[6:7]
	v_pk_mul_f32 v[16:17], v[16:17], v[8:9]
	v_lshl_add_u64 v[214:215], v[212:213], 0, s[4:5]
	v_pk_mul_f32 v[10:11], v[10:11], v[2:3]
	v_pk_mul_f32 v[12:13], v[12:13], v[4:5]
	v_cvt_pk_bf16_f32 v14, v14, v15
	v_cvt_pk_bf16_f32 v15, v16, v17
	v_cvt_pk_bf16_f32 v16, v10, v11
	v_cvt_pk_bf16_f32 v17, v12, v13
	global_store_dwordx4 v[214:215], v[14:17], off
	v_mov_b64_e32 v[2:3], v[146:147]
	s_mov_b64 s[4:5], s[22:23]
	s_and_b64 vcc, exec, s[38:39]
	s_cbranch_vccz .LBB0_815
	s_waitcnt vmcnt(0)
	s_cmpk_gt_u32 s2, 0xff
	v_readlane_b32 s89, v253, 39
	s_cbranch_scc1 .LBB0_14
	s_barrier
	s_branch .LBB0_14
